# adaLN partial-sum loop in the prologue rewritten: 16 w_ada rows in flight per thread instead of one load at a time (same fma order)
# speedup vs baseline: 1.0913x; 1.0292x over previous
.LBB0_1007:
	v_lshl_add_u64 v[32:33], v[14:15], 0, s[4:5]
	v_mov_b32_e32 v36, s7
	s_mov_b64 s[98:99], 0x6000
	ds_read_b128 v[66:69], v36
	ds_read_b128 v[70:73], v36 offset:16
	ds_read_b128 v[74:77], v36 offset:32
	ds_read_b128 v[78:81], v36 offset:48
	ds_read_b128 v[82:85], v36 offset:512
	ds_read_b128 v[86:89], v36 offset:528
	ds_read_b128 v[90:93], v36 offset:544
	ds_read_b128 v[94:97], v36 offset:560
	ds_read_b128 v[98:101], v36 offset:1024
	ds_read_b128 v[102:105], v36 offset:1040
	ds_read_b128 v[106:109], v36 offset:1056
	ds_read_b128 v[110:113], v36 offset:1072
	global_load_dword v50, v[32:33], off
	v_lshl_add_u64 v[32:33], v[32:33], 0, s[98:99]
	global_load_dword v51, v[32:33], off
	v_lshl_add_u64 v[32:33], v[32:33], 0, s[98:99]
	global_load_dword v52, v[32:33], off
	v_lshl_add_u64 v[32:33], v[32:33], 0, s[98:99]
	global_load_dword v53, v[32:33], off
	v_lshl_add_u64 v[32:33], v[32:33], 0, s[98:99]
	global_load_dword v54, v[32:33], off
	v_lshl_add_u64 v[32:33], v[32:33], 0, s[98:99]
	global_load_dword v55, v[32:33], off
	v_lshl_add_u64 v[32:33], v[32:33], 0, s[98:99]
	global_load_dword v56, v[32:33], off
	v_lshl_add_u64 v[32:33], v[32:33], 0, s[98:99]
	global_load_dword v57, v[32:33], off
	v_lshl_add_u64 v[32:33], v[32:33], 0, s[98:99]
	global_load_dword v58, v[32:33], off
	v_lshl_add_u64 v[32:33], v[32:33], 0, s[98:99]
	global_load_dword v59, v[32:33], off
	v_lshl_add_u64 v[32:33], v[32:33], 0, s[98:99]
	global_load_dword v60, v[32:33], off
	v_lshl_add_u64 v[32:33], v[32:33], 0, s[98:99]
	global_load_dword v61, v[32:33], off
	v_lshl_add_u64 v[32:33], v[32:33], 0, s[98:99]
	global_load_dword v62, v[32:33], off
	v_lshl_add_u64 v[32:33], v[32:33], 0, s[98:99]
	global_load_dword v63, v[32:33], off
	v_lshl_add_u64 v[32:33], v[32:33], 0, s[98:99]
	global_load_dword v64, v[32:33], off
	v_lshl_add_u64 v[32:33], v[32:33], 0, s[98:99]
	global_load_dword v65, v[32:33], off
	v_lshl_add_u64 v[32:33], v[32:33], 0, s[98:99]
	s_waitcnt lgkmcnt(0)
	s_waitcnt vmcnt(15)
	v_fmac_f32_e32 v19, v50, v66
	v_fmac_f32_e32 v17, v50, v82
	v_fmac_f32_e32 v16, v50, v98
	s_waitcnt vmcnt(14)
	v_fmac_f32_e32 v19, v51, v67
	v_fmac_f32_e32 v17, v51, v83
	v_fmac_f32_e32 v16, v51, v99
	s_waitcnt vmcnt(13)
	v_fmac_f32_e32 v19, v52, v68
	v_fmac_f32_e32 v17, v52, v84
	v_fmac_f32_e32 v16, v52, v100
	s_waitcnt vmcnt(12)
	v_fmac_f32_e32 v19, v53, v69
	v_fmac_f32_e32 v17, v53, v85
	v_fmac_f32_e32 v16, v53, v101
	s_waitcnt vmcnt(11)
	v_fmac_f32_e32 v19, v54, v70
	v_fmac_f32_e32 v17, v54, v86
	v_fmac_f32_e32 v16, v54, v102
	s_waitcnt vmcnt(10)
	v_fmac_f32_e32 v19, v55, v71
	v_fmac_f32_e32 v17, v55, v87
	v_fmac_f32_e32 v16, v55, v103
	s_waitcnt vmcnt(9)
	v_fmac_f32_e32 v19, v56, v72
	v_fmac_f32_e32 v17, v56, v88
	v_fmac_f32_e32 v16, v56, v104
	s_waitcnt vmcnt(8)
	v_fmac_f32_e32 v19, v57, v73
	v_fmac_f32_e32 v17, v57, v89
	v_fmac_f32_e32 v16, v57, v105
	s_waitcnt vmcnt(7)
	v_fmac_f32_e32 v19, v58, v74
	v_fmac_f32_e32 v17, v58, v90
	v_fmac_f32_e32 v16, v58, v106
	s_waitcnt vmcnt(6)
	v_fmac_f32_e32 v19, v59, v75
	v_fmac_f32_e32 v17, v59, v91
	v_fmac_f32_e32 v16, v59, v107
	s_waitcnt vmcnt(5)
	v_fmac_f32_e32 v19, v60, v76
	v_fmac_f32_e32 v17, v60, v92
	v_fmac_f32_e32 v16, v60, v108
	s_waitcnt vmcnt(4)
	v_fmac_f32_e32 v19, v61, v77
	v_fmac_f32_e32 v17, v61, v93
	v_fmac_f32_e32 v16, v61, v109
	s_waitcnt vmcnt(3)
	v_fmac_f32_e32 v19, v62, v78
	v_fmac_f32_e32 v17, v62, v94
	v_fmac_f32_e32 v16, v62, v110
	s_waitcnt vmcnt(2)
	v_fmac_f32_e32 v19, v63, v79
	v_fmac_f32_e32 v17, v63, v95
	v_fmac_f32_e32 v16, v63, v111
	s_waitcnt vmcnt(1)
	v_fmac_f32_e32 v19, v64, v80
	v_fmac_f32_e32 v17, v64, v96
	v_fmac_f32_e32 v16, v64, v112
	s_waitcnt vmcnt(0)
	v_fmac_f32_e32 v19, v65, v81
	v_fmac_f32_e32 v17, v65, v97
	v_fmac_f32_e32 v16, v65, v113
	s_add_i32 s7, s7, 64
	s_add_u32 s4, s4, 0x60000
	s_addc_u32 s5, s5, 0
	s_cmp_eq_u32 s4, 0x300000
	s_cbranch_scc0 .LBB0_1007
	s_mul_i32 s0, s0, 0x48000
	v_readlane_b32 s4, v253, 5
	v_readlane_b32 s5, v253, 6
	s_add_u32 s4, s4, s0
	s_mulk_i32 s6, 0x4800
	s_addc_u32 s5, s5, 0
	v_add_lshl_u32 v2, v18, s6, 2
	v_lshl_add_u64 v[4:5], s[4:5], 0, v[2:3]
	v_add_co_u32_e32 v6, vcc, 0x6000, v4
	global_store_dword v2, v19, s[4:5]
	s_nop 0
	v_addc_co_u32_e32 v7, vcc, 0, v5, vcc
	v_add_co_u32_e32 v4, vcc, 0xc000, v4
	global_store_dword v[6:7], v17, off
	s_nop 0
	v_addc_co_u32_e32 v5, vcc, 0, v5, vcc
	global_store_dword v[4:5], v16, off
	s_barrier
	s_mov_b64 s[4:5], 0
